# k32 + K/V stored by P4a as 16-key x 256 B chunks (4 KiB contiguous, residue-major) inside PROJ k|v columns; attention reads them there
# speedup vs baseline: 1.0092x; 1.0026x over previous
.LBB0_561:
	s_mul_i32 s98, s65, 171
	s_lshr_b32 s98, s98, 11
	s_mul_i32 s99, s98, 12
	s_sub_i32 s99, s65, s99
	s_cmp_lt_u32 s99, 4
	s_cbranch_scc1 .Lkv_q
	s_and_b32 s100, s46, 15
	s_lshl_b32 s100, s100, 8
	v_add_u32_e32 v209, s100, v1
	s_sub_i32 s99, s99, 4
	s_lshr_b32 s100, s99, 2
	s_and_b32 s99, s99, 3
	s_lshl_b32 s99, s99, 9
	s_lshl_b32 s100, s100, 13
	s_add_i32 s99, s99, s100
	s_lshr_b32 s100, s46, 4
	s_lshl_b32 s100, s100, 11
	s_add_i32 s99, s99, s100
	s_mul_i32 s100, s98, 0x1800
	s_addk_i32 s100, 0x800
	v_lshl_add_u32 v210, v162, 1, s100
	v_mov_b32_e32 v211, 0
	v_lshl_add_u64 v[210:211], s[36:37], 0, v[210:211]
	s_lshl_b32 s98, s98, 1
	s_sub_i32 s100, 12, s98
	s_lshl_b32 s101, 1, s98
	s_add_i32 s101, s101, -1
	v_add_u32_e32 v206, 0, v209
	v_and_b32_e32 v207, s101, v206
	v_lshlrev_b32_e32 v207, s100, v207
	v_lshrrev_b32_e32 v208, s98, v206
	v_or_b32_e32 v207, v207, v208
	v_lshrrev_b32_e32 v208, 4, v207
	v_add_u32_e32 v208, s99, v208
	v_and_b32_e32 v207, 15, v207
	v_mad_u64_u32 v[224:225], vcc, v208, s64, v[210:211]
	v_lshlrev_b32_e32 v207, 8, v207
	v_add_co_u32_e32 v224, vcc, v224, v207
	s_nop 0
	v_addc_co_u32_e32 v225, vcc, 0, v225, vcc
	v_add_co_u32_e32 v226, vcc, 0x900000, v224
	s_nop 0
	v_addc_co_u32_e32 v227, vcc, 0, v225, vcc
	v_add_u32_e32 v206, 16, v209
	v_and_b32_e32 v207, s101, v206
	v_lshlrev_b32_e32 v207, s100, v207
	v_lshrrev_b32_e32 v208, s98, v206
	v_or_b32_e32 v207, v207, v208
	v_lshrrev_b32_e32 v208, 4, v207
	v_add_u32_e32 v208, s99, v208
	v_and_b32_e32 v207, 15, v207
	v_mad_u64_u32 v[228:229], vcc, v208, s64, v[210:211]
	v_lshlrev_b32_e32 v207, 8, v207
	v_add_co_u32_e32 v228, vcc, v228, v207
	s_nop 0
	v_addc_co_u32_e32 v229, vcc, 0, v229, vcc
	v_add_co_u32_e32 v230, vcc, 0x900000, v228
	s_nop 0
	v_addc_co_u32_e32 v231, vcc, 0, v229, vcc
	v_add_u32_e32 v206, 32, v209
	v_and_b32_e32 v207, s101, v206
	v_lshlrev_b32_e32 v207, s100, v207
	v_lshrrev_b32_e32 v208, s98, v206
	v_or_b32_e32 v207, v207, v208
	v_lshrrev_b32_e32 v208, 4, v207
	v_add_u32_e32 v208, s99, v208
	v_and_b32_e32 v207, 15, v207
	v_mad_u64_u32 v[232:233], vcc, v208, s64, v[210:211]
	v_lshlrev_b32_e32 v207, 8, v207
	v_add_co_u32_e32 v232, vcc, v232, v207
	s_nop 0
	v_addc_co_u32_e32 v233, vcc, 0, v233, vcc
	v_add_co_u32_e32 v234, vcc, 0x900000, v232
	s_nop 0
	v_addc_co_u32_e32 v235, vcc, 0, v233, vcc
	v_add_u32_e32 v206, 48, v209
	v_and_b32_e32 v207, s101, v206
	v_lshlrev_b32_e32 v207, s100, v207
	v_lshrrev_b32_e32 v208, s98, v206
	v_or_b32_e32 v207, v207, v208
	v_lshrrev_b32_e32 v208, 4, v207
	v_add_u32_e32 v208, s99, v208
	v_and_b32_e32 v207, 15, v207
	v_mad_u64_u32 v[236:237], vcc, v208, s64, v[210:211]
	v_lshlrev_b32_e32 v207, 8, v207
	v_add_co_u32_e32 v236, vcc, v236, v207
	s_nop 0
	v_addc_co_u32_e32 v237, vcc, 0, v237, vcc
	v_add_co_u32_e32 v238, vcc, 0x900000, v236
	s_nop 0
	v_addc_co_u32_e32 v239, vcc, 0, v237, vcc
	v_add_u32_e32 v206, 0x80, v209
	v_and_b32_e32 v207, s101, v206
	v_lshlrev_b32_e32 v207, s100, v207
	v_lshrrev_b32_e32 v208, s98, v206
	v_or_b32_e32 v207, v207, v208
	v_lshrrev_b32_e32 v208, 4, v207
	v_add_u32_e32 v208, s99, v208
	v_and_b32_e32 v207, 15, v207
	v_mad_u64_u32 v[240:241], vcc, v208, s64, v[210:211]
	v_lshlrev_b32_e32 v207, 8, v207
	v_add_co_u32_e32 v240, vcc, v240, v207
	s_nop 0
	v_addc_co_u32_e32 v241, vcc, 0, v241, vcc
	v_add_co_u32_e32 v242, vcc, 0x900000, v240
	s_nop 0
	v_addc_co_u32_e32 v243, vcc, 0, v241, vcc
	v_add_u32_e32 v206, 0x90, v209
	v_and_b32_e32 v207, s101, v206
	v_lshlrev_b32_e32 v207, s100, v207
	v_lshrrev_b32_e32 v208, s98, v206
	v_or_b32_e32 v207, v207, v208
	v_lshrrev_b32_e32 v208, 4, v207
	v_add_u32_e32 v208, s99, v208
	v_and_b32_e32 v207, 15, v207
	v_mad_u64_u32 v[244:245], vcc, v208, s64, v[210:211]
	v_lshlrev_b32_e32 v207, 8, v207
	v_add_co_u32_e32 v244, vcc, v244, v207
	s_nop 0
	v_addc_co_u32_e32 v245, vcc, 0, v245, vcc
	v_add_co_u32_e32 v246, vcc, 0x900000, v244
	s_nop 0
	v_addc_co_u32_e32 v247, vcc, 0, v245, vcc
	v_add_u32_e32 v206, 0xa0, v209
	v_and_b32_e32 v207, s101, v206
	v_lshlrev_b32_e32 v207, s100, v207
	v_lshrrev_b32_e32 v208, s98, v206
	v_or_b32_e32 v207, v207, v208
	v_lshrrev_b32_e32 v208, 4, v207
	v_add_u32_e32 v208, s99, v208
	v_and_b32_e32 v207, 15, v207
	v_mad_u64_u32 v[248:249], vcc, v208, s64, v[210:211]
	v_lshlrev_b32_e32 v207, 8, v207
	v_add_co_u32_e32 v248, vcc, v248, v207
	s_nop 0
	v_addc_co_u32_e32 v249, vcc, 0, v249, vcc
	v_add_co_u32_e32 v250, vcc, 0x900000, v248
	s_nop 0
	v_addc_co_u32_e32 v251, vcc, 0, v249, vcc
	v_add_u32_e32 v206, 0xb0, v209
	v_and_b32_e32 v207, s101, v206
	v_lshlrev_b32_e32 v207, s100, v207
	v_lshrrev_b32_e32 v208, s98, v206
	v_or_b32_e32 v207, v207, v208
	v_lshrrev_b32_e32 v208, 4, v207
	v_add_u32_e32 v208, s99, v208
	v_and_b32_e32 v207, 15, v207
	v_mad_u64_u32 v[252:253], vcc, v208, s64, v[210:211]
	v_lshlrev_b32_e32 v207, 8, v207
	v_add_co_u32_e32 v252, vcc, v252, v207
	s_nop 0
	v_addc_co_u32_e32 v253, vcc, 0, v253, vcc
	v_add_co_u32_e32 v254, vcc, 0x900000, v252
	s_nop 0
	v_addc_co_u32_e32 v255, vcc, 0, v253, vcc
	s_branch .Lkv_done
.Lkv_q:
	v_lshl_add_u32 v209, s46, 8, v1
	v_lshl_or_b32 v210, s65, 8, v162
	v_lshlrev_b32_e32 v210, 1, v210
	v_mov_b32_e32 v211, 0
	v_lshl_add_u64 v[210:211], s[36:37], 0, v[210:211]
	v_add_u32_e32 v206, 0, v209
	v_mad_u64_u32 v[224:225], vcc, v206, s64, v[210:211]
	v_add_co_u32_e32 v226, vcc, 0x100, v224
	s_nop 0
	v_addc_co_u32_e32 v227, vcc, 0, v225, vcc
	v_add_u32_e32 v206, 16, v209
	v_mad_u64_u32 v[228:229], vcc, v206, s64, v[210:211]
	v_add_co_u32_e32 v230, vcc, 0x100, v228
	s_nop 0
	v_addc_co_u32_e32 v231, vcc, 0, v229, vcc
	v_add_u32_e32 v206, 32, v209
	v_mad_u64_u32 v[232:233], vcc, v206, s64, v[210:211]
	v_add_co_u32_e32 v234, vcc, 0x100, v232
	s_nop 0
	v_addc_co_u32_e32 v235, vcc, 0, v233, vcc
	v_add_u32_e32 v206, 48, v209
	v_mad_u64_u32 v[236:237], vcc, v206, s64, v[210:211]
	v_add_co_u32_e32 v238, vcc, 0x100, v236
	s_nop 0
	v_addc_co_u32_e32 v239, vcc, 0, v237, vcc
	v_add_u32_e32 v206, 0x80, v209
	v_mad_u64_u32 v[240:241], vcc, v206, s64, v[210:211]
	v_add_co_u32_e32 v242, vcc, 0x100, v240
	s_nop 0
	v_addc_co_u32_e32 v243, vcc, 0, v241, vcc
	v_add_u32_e32 v206, 0x90, v209
	v_mad_u64_u32 v[244:245], vcc, v206, s64, v[210:211]
	v_add_co_u32_e32 v246, vcc, 0x100, v244
	s_nop 0
	v_addc_co_u32_e32 v247, vcc, 0, v245, vcc
	v_add_u32_e32 v206, 0xa0, v209
	v_mad_u64_u32 v[248:249], vcc, v206, s64, v[210:211]
	v_add_co_u32_e32 v250, vcc, 0x100, v248
	s_nop 0
	v_addc_co_u32_e32 v251, vcc, 0, v249, vcc
	v_add_u32_e32 v206, 0xb0, v209
	v_mad_u64_u32 v[252:253], vcc, v206, s64, v[210:211]
	v_add_co_u32_e32 v254, vcc, 0x100, v252
	s_nop 0
	v_addc_co_u32_e32 v255, vcc, 0, v253, vcc
.Lkv_done:
	v_lshl_or_b32 v156, s65, 8, v162
	v_ashrrev_i32_e32 v157, 31, v156
	v_lshl_add_u32 v152, s46, 8, v1
	v_lshl_add_u64 v[150:151], v[156:157], 2, s[18:19]
	v_ashrrev_i32_e32 v153, 31, v152
	global_load_dwordx4 v[166:169], v[150:151], off offset:16
	global_load_dwordx4 v[158:161], v[150:151], off
	v_lshl_add_u64 v[148:149], v[152:153], 2, s[26:27]
	global_load_dword v153, v[148:149], off
	global_load_dword v190, v[148:149], off
	global_load_dword v192, v[148:149], off offset:64
	global_load_dword v194, v[148:149], off offset:128
	global_load_dword v196, v[148:149], off offset:192
	global_load_dword v198, v[148:149], off offset:512
	global_load_dword v200, v[148:149], off offset:576
	global_load_dword v202, v[148:149], off offset:640
	global_load_dword v204, v[148:149], off offset:704
	global_load_dwordx4 v[206:209], v[150:151], off offset:512
	global_load_dwordx4 v[210:213], v[150:151], off offset:528
	v_cvt_f32_i32_e32 v172, v126
	v_cvt_f32_i32_e32 v173, v127
	v_cvt_f32_i32_e32 v174, v128
	v_cvt_f32_i32_e32 v175, v129
	v_cvt_f32_i32_e32 v176, v122
	v_cvt_f32_i32_e32 v177, v123
	v_cvt_f32_i32_e32 v178, v124
	v_cvt_f32_i32_e32 v179, v125
	v_mov_b64_e32 v[154:155], s[36:37]
	v_or_b32_e32 v170, 16, v152
	v_lshlrev_b64 v[128:129], 1, v[156:157]
	s_nop 0
	v_ashrrev_i32_e32 v171, 31, v170
	s_nop 0
	v_lshl_add_u64 v[124:125], v[170:171], 2, s[26:27]
	v_cvt_f32_i32_e32 v118, v118
	v_cvt_f32_i32_e32 v119, v119
	v_cvt_f32_i32_e32 v120, v120
	v_cvt_f32_i32_e32 v121, v121
	v_cvt_f32_i32_e32 v110, v110
	v_cvt_f32_i32_e32 v111, v111
	v_cvt_f32_i32_e32 v112, v112
	v_cvt_f32_i32_e32 v113, v113
	v_cvt_f32_i32_e32 v102, v102
	v_cvt_f32_i32_e32 v103, v103
	v_cvt_f32_i32_e32 v104, v104
	v_cvt_f32_i32_e32 v105, v105
	v_cvt_f32_i32_e32 v100, v100
	v_cvt_f32_i32_e32 v101, v101
	v_cvt_f32_i32_e32 v94, v94
	v_cvt_f32_i32_e32 v95, v95
	v_cvt_f32_i32_e32 v96, v96
	v_cvt_f32_i32_e32 v97, v97
	v_cvt_f32_i32_e32 v92, v92
	v_cvt_f32_i32_e32 v93, v93
	v_cvt_f32_i32_e32 v86, v86
	v_cvt_f32_i32_e32 v87, v87
	v_cvt_f32_i32_e32 v88, v88
	v_cvt_f32_i32_e32 v89, v89
	v_cvt_f32_i32_e32 v84, v84
	v_cvt_f32_i32_e32 v85, v85
	v_cvt_f32_i32_e32 v78, v78
	v_cvt_f32_i32_e32 v79, v79
	v_cvt_f32_i32_e32 v80, v80
	v_cvt_f32_i32_e32 v81, v81
	v_cvt_f32_i32_e32 v76, v76
	v_cvt_f32_i32_e32 v77, v77
	v_cvt_f32_i32_e32 v70, v70
	v_cvt_f32_i32_e32 v71, v71
	v_cvt_f32_i32_e32 v72, v72
	v_cvt_f32_i32_e32 v73, v73
	v_cvt_f32_i32_e32 v64, v64
	v_cvt_f32_i32_e32 v65, v65
	v_cvt_f32_i32_e32 v69, v69
	v_cvt_f32_i32_e32 v68, v68
	v_cvt_f32_i32_e32 v53, v53
	v_cvt_f32_i32_e32 v54, v54
	v_cvt_f32_i32_e32 v55, v55
	v_cvt_f32_i32_e32 v56, v56
	v_cvt_f32_i32_e32 v57, v57
	v_cvt_f32_i32_e32 v50, v50
	v_cvt_f32_i32_e32 v51, v51
	v_cvt_f32_i32_e32 v52, v52
	v_cvt_f32_i32_e32 v45, v45
	v_cvt_f32_i32_e32 v46, v46
	v_cvt_f32_i32_e32 v47, v47
	v_cvt_f32_i32_e32 v48, v48
	v_cvt_f32_i32_e32 v49, v49
	v_cvt_f32_i32_e32 v42, v42
	v_cvt_f32_i32_e32 v43, v43
	v_cvt_f32_i32_e32 v44, v44
	v_cvt_f32_i32_e32 v37, v37
	v_cvt_f32_i32_e32 v38, v38
	v_cvt_f32_i32_e32 v39, v39
	v_cvt_f32_i32_e32 v40, v40
	s_cmp_lg_u64 s[24:25], 0
	s_cbranch_scc0 .Lalb_3
	s_barrier
.Lalb_3:
	s_waitcnt vmcnt(0)
	v_pk_mul_f32 v[126:127], v[168:169], s[38:39] op_sel_hi:[1,0]
	v_pk_mul_f32 v[156:157], v[160:161], s[38:39] op_sel_hi:[1,0]
	v_pk_mul_f32 v[160:161], v[158:159], s[38:39] op_sel_hi:[1,0]
	v_pk_mul_f32 v[158:159], v[166:167], s[38:39] op_sel_hi:[1,0]
	v_mul_f32_e32 v166, v160, v153
	v_mul_f32_e32 v167, v161, v153
	v_mul_f32_e32 v168, v156, v153
	v_mul_f32_e32 v169, v157, v153
	v_mul_f32_e32 v171, v153, v158
	v_mul_f32_e32 v180, v153, v159
	v_mul_f32_e32 v181, v153, v126
	v_mul_f32_e32 v153, v153, v127
	v_mul_f32_e32 v166, v166, v172
	v_mul_f32_e32 v167, v167, v173
	v_mul_f32_e32 v168, v168, v174
	v_mul_f32_e32 v169, v169, v175
	v_mul_f32_e32 v171, v171, v176
	v_mul_f32_e32 v172, v180, v177
	v_mul_f32_e32 v173, v181, v178
	v_mul_f32_e32 v153, v153, v179
	v_cvt_pk_bf16_f32 v166, v166, v167
	v_cvt_pk_bf16_f32 v167, v168, v169
	v_cvt_pk_bf16_f32 v168, v171, v172
	v_cvt_pk_bf16_f32 v169, v173, v153
	global_store_dwordx4 v[224:225], v[166:169], off
	s_nop 1
	v_cvt_f32_i32_e32 v171, v116
	v_cvt_f32_i32_e32 v168, v114
	v_cvt_f32_i32_e32 v169, v115
	v_cvt_f32_i32_e32 v172, v117
	v_or_b32_e32 v166, 32, v152
	v_ashrrev_i32_e32 v167, 31, v166
	s_nop 0
	v_lshl_add_u64 v[116:117], v[166:167], 2, s[26:27]
	s_nop 0
	v_cvt_f32_i32_e32 v41, v41
	v_cvt_f32_i32_e32 v34, v34
	v_cvt_f32_i32_e32 v35, v35
	v_cvt_f32_i32_e32 v36, v36
	v_cvt_f32_i32_e32 v29, v29
	v_cvt_f32_i32_e32 v30, v30
	v_cvt_f32_i32_e32 v31, v31
	v_cvt_f32_i32_e32 v32, v32
	v_cvt_f32_i32_e32 v33, v33
	v_cvt_f32_i32_e32 v26, v26
	v_cvt_f32_i32_e32 v27, v27
	v_cvt_f32_i32_e32 v28, v28
	v_cvt_f32_i32_e32 v21, v21
	v_cvt_f32_i32_e32 v22, v22
	v_cvt_f32_i32_e32 v23, v23
	v_cvt_f32_i32_e32 v24, v24
	v_cvt_f32_i32_e32 v25, v25
	v_cvt_f32_i32_e32 v18, v18
	v_cvt_f32_i32_e32 v19, v19
	v_cvt_f32_i32_e32 v20, v20
	v_cvt_f32_i32_e32 v13, v13
	v_cvt_f32_i32_e32 v14, v14
	v_cvt_f32_i32_e32 v15, v15
	v_cvt_f32_i32_e32 v16, v16
	v_cvt_f32_i32_e32 v17, v17
	v_cvt_f32_i32_e32 v10, v10
	v_cvt_f32_i32_e32 v11, v11
	v_cvt_f32_i32_e32 v12, v12
	v_cvt_f32_i32_e32 v5, v5
	v_cvt_f32_i32_e32 v6, v6
	v_cvt_f32_i32_e32 v7, v7
	v_cvt_f32_i32_e32 v8, v8
	v_cvt_f32_i32_e32 v9, v9
	v_cvt_f32_i32_e32 v2, v2
	v_cvt_f32_i32_e32 v3, v3
	v_cvt_f32_i32_e32 v4, v4
	s_and_b64 vcc, exec, s[4:5]
	v_mov_b32_e32 v153, v192
	v_mul_f32_e32 v167, v160, v153
	v_mul_f32_e32 v170, v161, v153
	v_mul_f32_e32 v173, v156, v153
	v_mul_f32_e32 v174, v157, v153
	v_mul_f32_e32 v175, v158, v153
	v_mul_f32_e32 v176, v159, v153
	v_mul_f32_e32 v177, v126, v153
	v_mul_f32_e32 v153, v127, v153
	v_mul_f32_e32 v118, v167, v118
	v_mul_f32_e32 v119, v170, v119
	v_mul_f32_e32 v120, v173, v120
	v_mul_f32_e32 v121, v174, v121
	v_mul_f32_e32 v167, v175, v168
	v_mul_f32_e32 v168, v176, v169
	v_mul_f32_e32 v169, v177, v171
	v_mul_f32_e32 v153, v153, v172
	v_cvt_pk_bf16_f32 v118, v118, v119
	v_cvt_pk_bf16_f32 v119, v120, v121
	v_cvt_pk_bf16_f32 v120, v167, v168
	v_cvt_pk_bf16_f32 v121, v169, v153
	global_store_dwordx4 v[228:229], v[118:121], off
	s_nop 1
	v_cvt_f32_i32_e32 v153, v107
	v_cvt_f32_i32_e32 v121, v106
	v_cvt_f32_i32_e32 v167, v108
	v_cvt_f32_i32_e32 v168, v109
	v_or_b32_e32 v118, 48, v152
	v_ashrrev_i32_e32 v119, 31, v118
	s_nop 0
	v_lshl_add_u64 v[108:109], v[118:119], 2, s[26:27]
	s_nop 0
	v_mov_b32_e32 v120, v194
	v_mul_f32_e32 v119, v160, v120
	v_mul_f32_e32 v166, v161, v120
	v_mul_f32_e32 v169, v156, v120
	v_mul_f32_e32 v170, v157, v120
	v_mul_f32_e32 v171, v158, v120
	v_mul_f32_e32 v172, v159, v120
	v_mul_f32_e32 v173, v126, v120
	v_mul_f32_e32 v120, v127, v120
	v_mul_f32_e32 v110, v119, v110
	v_mul_f32_e32 v111, v166, v111
	v_mul_f32_e32 v112, v169, v112
	v_mul_f32_e32 v113, v170, v113
	v_mul_f32_e32 v119, v171, v121
	v_mul_f32_e32 v121, v172, v153
	v_mul_f32_e32 v153, v173, v167
	v_mul_f32_e32 v120, v120, v168
	v_cvt_pk_bf16_f32 v110, v110, v111
	v_cvt_pk_bf16_f32 v111, v112, v113
	v_cvt_pk_bf16_f32 v112, v119, v121
	v_cvt_pk_bf16_f32 v113, v153, v120
	global_store_dwordx4 v[232:233], v[110:113], off
	s_nop 1
	v_mov_b32_e32 v110, v196
	v_mul_f32_e32 v119, v156, v110
	v_cvt_f32_i32_e32 v111, v98
	v_cvt_f32_i32_e32 v112, v99
	s_nop 0
	v_mul_f32_e32 v113, v160, v110
	v_mul_f32_e32 v118, v161, v110
	s_nop 0
	v_mul_f32_e32 v120, v157, v110
	v_mul_f32_e32 v121, v158, v110
	v_mul_f32_e32 v153, v159, v110
	v_mul_f32_e32 v166, v126, v110
	v_mul_f32_e32 v110, v127, v110
	v_mul_f32_e32 v102, v113, v102
	v_mul_f32_e32 v103, v118, v103
	v_mul_f32_e32 v104, v119, v104
	v_mul_f32_e32 v105, v120, v105
	v_mul_f32_e32 v111, v121, v111
	v_mul_f32_e32 v112, v153, v112
	v_mul_f32_e32 v113, v166, v100
	v_mul_f32_e32 v110, v110, v101
	v_cvt_pk_bf16_f32 v100, v102, v103
	v_cvt_pk_bf16_f32 v101, v104, v105
	v_cvt_pk_bf16_f32 v102, v111, v112
	v_cvt_pk_bf16_f32 v103, v113, v110
	global_store_dwordx4 v[236:237], v[100:103], off
	s_nop 1
	v_mov_b32_e32 v100, v198
	v_mul_f32_e32 v104, v161, v100
	v_cvt_f32_i32_e32 v101, v90
	v_cvt_f32_i32_e32 v102, v91
	v_add_u32_e32 v90, 0x80, v152
	s_nop 0
	v_mul_f32_e32 v103, v160, v100
	s_nop 0
	v_mul_f32_e32 v105, v156, v100
	v_mul_f32_e32 v110, v157, v100
	v_mul_f32_e32 v111, v158, v100
	v_mul_f32_e32 v112, v159, v100
	v_mul_f32_e32 v113, v126, v100
	v_mul_f32_e32 v100, v127, v100
	v_mul_f32_e32 v94, v103, v94
	v_mul_f32_e32 v95, v104, v95
	v_mul_f32_e32 v96, v105, v96
	v_mul_f32_e32 v97, v110, v97
	v_mul_f32_e32 v101, v111, v101
	v_mul_f32_e32 v102, v112, v102
	v_mul_f32_e32 v103, v113, v92
	v_mul_f32_e32 v100, v100, v93
	v_cvt_pk_bf16_f32 v92, v94, v95
	v_cvt_pk_bf16_f32 v93, v96, v97
	v_cvt_pk_bf16_f32 v94, v101, v102
	v_cvt_pk_bf16_f32 v95, v103, v100
	global_store_dwordx4 v[240:241], v[92:95], off
	s_nop 1
	v_mov_b32_e32 v92, v200
	v_mul_f32_e32 v96, v161, v92
	v_cvt_f32_i32_e32 v93, v82
	v_cvt_f32_i32_e32 v94, v83
	v_add_u32_e32 v82, 0x90, v152
	s_nop 0
	v_mul_f32_e32 v95, v160, v92
	s_nop 0
	v_mul_f32_e32 v97, v156, v92
	v_mul_f32_e32 v100, v157, v92
	v_mul_f32_e32 v101, v158, v92
	v_mul_f32_e32 v102, v159, v92
	v_mul_f32_e32 v103, v126, v92
	v_mul_f32_e32 v92, v127, v92
	v_mul_f32_e32 v86, v95, v86
	v_mul_f32_e32 v87, v96, v87
	v_mul_f32_e32 v88, v97, v88
	v_mul_f32_e32 v89, v100, v89
	v_mul_f32_e32 v93, v101, v93
	v_mul_f32_e32 v94, v102, v94
	v_mul_f32_e32 v95, v103, v84
	v_mul_f32_e32 v92, v92, v85
	v_cvt_pk_bf16_f32 v84, v86, v87
	v_cvt_pk_bf16_f32 v85, v88, v89
	v_cvt_pk_bf16_f32 v86, v93, v94
	v_cvt_pk_bf16_f32 v87, v95, v92
	global_store_dwordx4 v[244:245], v[84:87], off
	s_nop 1
	v_mov_b32_e32 v84, v202
	v_mul_f32_e32 v88, v161, v84
	v_cvt_f32_i32_e32 v85, v74
	v_cvt_f32_i32_e32 v86, v75
	v_add_u32_e32 v74, 0xa0, v152
	s_nop 0
	v_mul_f32_e32 v87, v160, v84
	s_nop 0
	v_mul_f32_e32 v89, v156, v84
	v_mul_f32_e32 v92, v157, v84
	v_mul_f32_e32 v93, v158, v84
	v_mul_f32_e32 v94, v159, v84
	v_mul_f32_e32 v95, v126, v84
	v_mul_f32_e32 v84, v127, v84
	v_mul_f32_e32 v78, v87, v78
	v_mul_f32_e32 v79, v88, v79
	v_mul_f32_e32 v80, v89, v80
	v_mul_f32_e32 v81, v92, v81
	v_mul_f32_e32 v85, v93, v85
	v_mul_f32_e32 v86, v94, v86
	v_mul_f32_e32 v87, v95, v76
	v_mul_f32_e32 v84, v84, v77
	v_cvt_pk_bf16_f32 v76, v78, v79
	v_cvt_pk_bf16_f32 v77, v80, v81
	v_cvt_pk_bf16_f32 v78, v85, v86
	v_cvt_pk_bf16_f32 v79, v87, v84
	global_store_dwordx4 v[248:249], v[76:79], off
	s_nop 1
	v_cvt_f32_i32_e32 v88, v61
	v_cvt_f32_i32_e32 v77, v62
	v_cvt_f32_i32_e32 v78, v63
	v_add_u32_e32 v62, 0xb0, v152
	s_nop 0
	s_nop 0
	s_mov_b64 s[0:1], -1
	v_mov_b32_e32 v76, v204
	v_mul_f32_e32 v79, v160, v76
	v_mul_f32_e32 v80, v161, v76
	v_mul_f32_e32 v81, v156, v76
	v_mul_f32_e32 v84, v157, v76
	v_mul_f32_e32 v85, v158, v76
	v_mul_f32_e32 v86, v159, v76
	v_mul_f32_e32 v87, v126, v76
	v_mul_f32_e32 v76, v127, v76
	v_mul_f32_e32 v70, v79, v70
	v_mul_f32_e32 v71, v80, v71
	v_mul_f32_e32 v72, v81, v72
	v_mul_f32_e32 v73, v84, v73
	v_mul_f32_e32 v77, v85, v77
	v_mul_f32_e32 v78, v86, v78
	v_mul_f32_e32 v64, v87, v64
	v_mul_f32_e32 v65, v76, v65
	v_cvt_pk_bf16_f32 v70, v70, v71
	v_cvt_pk_bf16_f32 v71, v72, v73
	v_cvt_pk_bf16_f32 v72, v77, v78
	v_cvt_pk_bf16_f32 v73, v64, v65
	global_store_dwordx4 v[252:253], v[70:73], off
	s_nop 1
	s_nop 1
	v_cvt_f32_i32_e32 v81, v66
	v_cvt_f32_i32_e32 v84, v67
	v_cvt_f32_i32_e32 v85, v58
	v_cvt_f32_i32_e32 v86, v59
	v_cvt_f32_i32_e32 v87, v60
	v_pk_mul_f32 v[60:61], v[208:209], s[38:39] op_sel_hi:[1,0]
	v_pk_mul_f32 v[66:67], v[206:207], s[38:39] op_sel_hi:[1,0]
	v_pk_mul_f32 v[58:59], v[212:213], s[38:39] op_sel_hi:[1,0]
	v_pk_mul_f32 v[64:65], v[210:211], s[38:39] op_sel_hi:[1,0]
	v_mov_b32_e32 v80, v190
	v_mul_f32_e32 v70, v66, v80
	v_mul_f32_e32 v71, v67, v80
	v_mul_f32_e32 v73, v61, v80
	v_mul_f32_e32 v72, v60, v80
	v_mul_f32_e32 v76, v80, v64
	v_mul_f32_e32 v77, v80, v65
	v_mul_f32_e32 v78, v80, v58
	v_mul_f32_e32 v79, v80, v59
	v_mul_f32_e32 v70, v70, v81
	v_mul_f32_e32 v71, v71, v84
	v_mul_f32_e32 v69, v73, v69
	v_mul_f32_e32 v72, v72, v68
	v_mul_f32_e32 v73, v76, v85
	v_mul_f32_e32 v76, v77, v86
	v_mul_f32_e32 v77, v78, v87
	v_mul_f32_e32 v78, v79, v88
	v_cvt_pk_bf16_f32 v68, v70, v71
	v_cvt_pk_bf16_f32 v69, v72, v69
	v_cvt_pk_bf16_f32 v70, v73, v76
	v_cvt_pk_bf16_f32 v71, v77, v78
	global_store_dwordx4 v[226:227], v[68:71], off
	s_nop 1
	v_mov_b32_e32 v68, v192
	v_mul_f32_e32 v72, v61, v68
	v_mul_f32_e32 v69, v66, v68
	v_mul_f32_e32 v70, v67, v68
	v_mul_f32_e32 v71, v60, v68
	v_mul_f32_e32 v73, v64, v68
	v_mul_f32_e32 v76, v65, v68
	v_mul_f32_e32 v77, v58, v68
	v_mul_f32_e32 v68, v59, v68
	v_mul_f32_e32 v53, v68, v53
	v_mul_f32_e32 v54, v69, v54
	v_mul_f32_e32 v55, v70, v55
	v_mul_f32_e32 v56, v71, v56
	v_mul_f32_e32 v57, v72, v57
	v_mul_f32_e32 v69, v73, v50
	v_mul_f32_e32 v70, v76, v51
	v_mul_f32_e32 v71, v77, v52
	v_cvt_pk_bf16_f32 v50, v54, v55
	v_cvt_pk_bf16_f32 v51, v56, v57
	v_cvt_pk_bf16_f32 v52, v69, v70
	v_cvt_pk_bf16_f32 v53, v71, v53
	global_store_dwordx4 v[230:231], v[50:53], off
	s_nop 1
	v_mov_b32_e32 v50, v194
	v_mul_f32_e32 v54, v61, v50
	v_mul_f32_e32 v51, v66, v50
	v_mul_f32_e32 v52, v67, v50
	v_mul_f32_e32 v53, v60, v50
	v_mul_f32_e32 v55, v64, v50
	v_mul_f32_e32 v56, v65, v50
	v_mul_f32_e32 v57, v58, v50
	v_mul_f32_e32 v50, v59, v50
	v_mul_f32_e32 v45, v50, v45
	v_mul_f32_e32 v46, v51, v46
	v_mul_f32_e32 v47, v52, v47
	v_mul_f32_e32 v48, v53, v48
	v_mul_f32_e32 v49, v54, v49
	v_mul_f32_e32 v51, v55, v42
	v_mul_f32_e32 v52, v56, v43
	v_mul_f32_e32 v53, v57, v44
	v_cvt_pk_bf16_f32 v42, v46, v47
	v_cvt_pk_bf16_f32 v43, v48, v49
	v_cvt_pk_bf16_f32 v44, v51, v52
	v_cvt_pk_bf16_f32 v45, v53, v45
	global_store_dwordx4 v[234:235], v[42:45], off
	s_nop 1
	v_mov_b32_e32 v42, v196
	v_mul_f32_e32 v46, v61, v42
	v_mul_f32_e32 v43, v66, v42
	v_mul_f32_e32 v44, v67, v42
	v_mul_f32_e32 v45, v60, v42
	v_mul_f32_e32 v47, v64, v42
	v_mul_f32_e32 v48, v65, v42
	v_mul_f32_e32 v49, v58, v42
	v_mul_f32_e32 v42, v59, v42
	v_mul_f32_e32 v37, v42, v37
	v_mul_f32_e32 v38, v43, v38
	v_mul_f32_e32 v39, v44, v39
	v_mul_f32_e32 v40, v45, v40
	v_mul_f32_e32 v41, v46, v41
	v_mul_f32_e32 v43, v47, v34
	v_mul_f32_e32 v44, v48, v35
	v_mul_f32_e32 v45, v49, v36
	v_cvt_pk_bf16_f32 v34, v38, v39
	v_cvt_pk_bf16_f32 v35, v40, v41
	v_cvt_pk_bf16_f32 v36, v43, v44
	v_cvt_pk_bf16_f32 v37, v45, v37
	global_store_dwordx4 v[238:239], v[34:37], off
	s_nop 1
	v_mov_b32_e32 v34, v198
	v_mul_f32_e32 v38, v61, v34
	v_mul_f32_e32 v35, v66, v34
	v_mul_f32_e32 v36, v67, v34
	v_mul_f32_e32 v37, v60, v34
	v_mul_f32_e32 v39, v64, v34
	v_mul_f32_e32 v40, v65, v34
	v_mul_f32_e32 v41, v58, v34
	v_mul_f32_e32 v34, v59, v34
	v_mul_f32_e32 v29, v34, v29
	v_mul_f32_e32 v30, v35, v30
	v_mul_f32_e32 v31, v36, v31
	v_mul_f32_e32 v32, v37, v32
	v_mul_f32_e32 v33, v38, v33
	v_mul_f32_e32 v35, v39, v26
	v_mul_f32_e32 v36, v40, v27
	v_mul_f32_e32 v37, v41, v28
	v_cvt_pk_bf16_f32 v26, v30, v31
	v_cvt_pk_bf16_f32 v27, v32, v33
	v_cvt_pk_bf16_f32 v28, v35, v36
	v_cvt_pk_bf16_f32 v29, v37, v29
	global_store_dwordx4 v[242:243], v[26:29], off
	s_nop 1
	v_mov_b32_e32 v26, v200
	v_mul_f32_e32 v30, v61, v26
	v_mul_f32_e32 v27, v66, v26
	v_mul_f32_e32 v28, v67, v26
	v_mul_f32_e32 v29, v60, v26
	v_mul_f32_e32 v31, v64, v26
	v_mul_f32_e32 v32, v65, v26
	v_mul_f32_e32 v33, v58, v26
	v_mul_f32_e32 v26, v59, v26
	v_mul_f32_e32 v21, v26, v21
	v_mul_f32_e32 v22, v27, v22
	v_mul_f32_e32 v23, v28, v23
	v_mul_f32_e32 v24, v29, v24
	v_mul_f32_e32 v25, v30, v25
	v_mul_f32_e32 v27, v31, v18
	v_mul_f32_e32 v28, v32, v19
	v_mul_f32_e32 v29, v33, v20
	v_cvt_pk_bf16_f32 v18, v22, v23
	v_cvt_pk_bf16_f32 v19, v24, v25
	v_cvt_pk_bf16_f32 v20, v27, v28
	v_cvt_pk_bf16_f32 v21, v29, v21
	global_store_dwordx4 v[246:247], v[18:21], off
	s_nop 1
	v_mov_b32_e32 v18, v202
	v_mul_f32_e32 v22, v61, v18
	v_mul_f32_e32 v19, v66, v18
	v_mul_f32_e32 v20, v67, v18
	v_mul_f32_e32 v21, v60, v18
	v_mul_f32_e32 v23, v64, v18
	v_mul_f32_e32 v24, v65, v18
	v_mul_f32_e32 v25, v58, v18
	v_mul_f32_e32 v18, v59, v18
	v_mul_f32_e32 v13, v18, v13
	v_mul_f32_e32 v14, v19, v14
	v_mul_f32_e32 v15, v20, v15
	v_mul_f32_e32 v16, v21, v16
	v_mul_f32_e32 v17, v22, v17
	v_mul_f32_e32 v19, v23, v10
	v_mul_f32_e32 v20, v24, v11
	v_mul_f32_e32 v21, v25, v12
	v_cvt_pk_bf16_f32 v10, v14, v15
	v_cvt_pk_bf16_f32 v11, v16, v17
	v_cvt_pk_bf16_f32 v12, v19, v20
	v_cvt_pk_bf16_f32 v13, v21, v13
	global_store_dwordx4 v[250:251], v[10:13], off
	s_nop 1
	v_mov_b32_e32 v10, v204
	v_mul_f32_e32 v14, v61, v10
	v_mul_f32_e32 v11, v66, v10
	v_mul_f32_e32 v12, v67, v10
	v_mul_f32_e32 v13, v60, v10
	v_mul_f32_e32 v15, v64, v10
	v_mul_f32_e32 v16, v65, v10
	v_mul_f32_e32 v17, v58, v10
	v_mul_f32_e32 v10, v59, v10
	v_mul_f32_e32 v5, v10, v5
	v_mul_f32_e32 v6, v11, v6
	v_mul_f32_e32 v7, v12, v7
	v_mul_f32_e32 v8, v13, v8
	v_mul_f32_e32 v9, v14, v9
	v_mul_f32_e32 v11, v15, v2
	v_mul_f32_e32 v12, v16, v3
	v_mul_f32_e32 v13, v17, v4
	v_cvt_pk_bf16_f32 v2, v6, v7
	v_cvt_pk_bf16_f32 v3, v8, v9
	v_cvt_pk_bf16_f32 v4, v11, v12
	v_cvt_pk_bf16_f32 v5, v13, v5
	global_store_dwordx4 v[254:255], v[2:5], off
	s_cbranch_vccnz .LBB0_552
	s_andn2_b64 vcc, exec, s[16:17]
	s_cbranch_vccnz .LBB0_551
	s_barrier
	s_branch .LBB0_551

.LBB0_671:
	s_cmp_lt_i32 s94, 6
	s_cselect_b64 s[4:5], -1, 0
	s_add_u32 s38, s14, 0x2c600000
	s_addc_u32 s39, s15, 0
	s_add_u32 s72, s14, 0x5be00000
	s_addc_u32 s73, s15, 0
	s_and_b64 s[24:25], s[4:5], s[0:1]
	s_andn2_b64 vcc, exec, s[24:25]
	v_writelane_b32 v222, s72, 8
	s_nop 1
	v_writelane_b32 v222, s73, 9
	s_cbranch_vccnz .LBB0_1026
	v_writelane_b32 v222, s24, 10
	v_mov_b32_e32 v1, v0
	s_nop 0
	v_writelane_b32 v222, s25, 11
	v_writelane_b32 v222, s91, 12
	v_writelane_b32 v222, s96, 13
	s_nop 1
	v_writelane_b32 v222, s97, 14
	v_writelane_b32 v222, s94, 15
	s_nop 1
	v_writelane_b32 v222, s95, 16
	v_writelane_b32 v222, s92, 17
	s_nop 1
	v_writelane_b32 v222, s93, 18
	v_writelane_b32 v222, s90, 19
	s_nop 0
	v_readlane_b32 s0, v222, 2
	s_cmpk_gt_i32 s0, 0xbff
	v_readfirstlane_b32 s0, v1
	s_cbranch_scc1 .LBB0_960
	s_add_u32 s4, s14, 0x32600000
	s_addc_u32 s5, s15, 0
	s_ashr_i32 s8, s0, 6
	s_sub_i32 s1, 11, s8
	v_writelane_b32 v222, s4, 20
	s_cmp_lt_i32 s8, 4
	s_cselect_b32 s1, s8, s1
	v_writelane_b32 v222, s5, 21
	s_ashr_i32 s0, s0, 1
	v_writelane_b32 v222, s1, 22
	s_andn2_b32 s0, s0, 63
	v_bfe_u32 v2, v1, 2, 2
	v_lshl_or_b32 v3, v2, 4, s0
	s_lshl_b32 s0, s8, 3
	v_readlane_b32 s54, v222, 2
	v_and_b32_e32 v40, 15, v1
	v_bfe_u32 v41, v1, 4, 2
	v_and_or_b32 v42, s0, 8, v3
	v_lshlrev_b32_e32 v4, 2, v1
	s_ashr_i32 s0, s54, 9
	v_lshlrev_b32_e32 v118, 4, v41
	v_lshlrev_b32_e32 v3, 6, v40
	v_and_b32_e32 v4, 32, v4
	s_and_b32 s0, s0, -2
	v_bitop3_b32 v43, v118, v4, v3 bitop3:0x36
	v_lshlrev_b32_e32 v3, 4, v1
	s_sub_i32 s0, 5, s0
	v_lshl_or_b32 v125, s1, 4, v40
	v_add_u32_e32 v4, 0x2000, v3
	s_and_b32 s1, s54, 31
	s_lshl_b32 s0, -1, s0
	s_lshl_b32 s3, s8, 10
	v_ashrrev_i32_e32 v5, 31, v4
	s_andn2_b32 s0, s1, s0
	v_lshrrev_b32_e32 v5, 22, v5
	s_cmp_eq_u32 s0, 0
	v_add_u32_e32 v5, v4, v5
	s_cselect_b64 s[6:7], -1, 0
	s_ashr_i32 s4, s54, 10
	v_ashrrev_i32_e32 v5, 10, v5
	s_lshl_b32 s10, s4, 1
	v_mul_i32_i24_e32 v7, 0x400, v5
	s_sub_i32 s0, 5, s10
	v_sub_u32_e32 v4, v4, v7
	s_lshl_b32 s5, -1, s0
	s_lshl_b32 s9, s54, 4
	v_lshrrev_b32_e32 v7, 4, v4
	s_andn2_b32 s11, s1, s5
	s_lshr_b32 s5, s1, s0
	s_and_b32 s9, s9, 0x3000
	v_bitop3_b32 v4, v7, v4, 32 bitop3:0x6c
	s_or_b32 s5, s5, s9
	v_ashrrev_i32_e32 v7, 31, v4
	s_lshl_b64 s[0:1], 0x4800, s10
	s_mul_i32 s5, s5, 0x9000
	v_lshrrev_b32_e32 v7, 26, v7
	s_add_u32 s9, s36, s5
	s_mulk_i32 s4, 0xc00
	v_add_u32_e32 v7, v4, v7
	s_addc_u32 s16, s37, 0
	s_ashr_i32 s5, s4, 31
	v_ashrrev_i32_e32 v8, 6, v7
	v_and_b32_e32 v7, 0xc0, v7
	s_lshl_b64 s[4:5], s[4:5], 1
	v_lshlrev_b32_e32 v6, 5, v5
	v_sub_u32_e32 v4, v4, v7
	v_mov_b32_e32 v10, 1
	s_add_u32 s4, s9, s4
	v_and_b32_e32 v6, 32, v6
	v_ashrrev_i16_sdwa v4, v10, sext(v4) dst_sel:DWORD dst_unused:UNUSED_PAD src0_sel:DWORD src1_sel:BYTE_0
	s_addc_u32 s5, s16, s5
	s_and_b32 s9, s66, 0x700
	v_add_u32_sdwa v122, v6, sext(v4) dst_sel:DWORD dst_unused:UNUSED_PAD src0_sel:DWORD src1_sel:WORD_0
	v_lshlrev_b32_e32 v4, 3, v5
	s_add_u32 s4, s4, s9
	v_and_b32_e32 v4, -16, v4
	s_addc_u32 s5, s5, 0
	v_add_u32_e32 v124, v8, v4
	v_ashrrev_i32_e32 v4, 31, v1
	s_cmp_lg_u64 s[6:7], 0
	v_lshlrev_b32_e32 v120, 2, v41
	v_lshrrev_b32_e32 v4, 26, v4
	v_cndmask_b32_e64 v13, 0, 1, s[6:7]
	s_addc_u32 s6, s11, 0
	v_and_or_b32 v44, v1, 3, v120
	v_add_u32_e32 v4, v1, v4
	v_bfe_i32 v1, v1, 27, 1
	s_lshl_b32 s6, s6, 7
	v_lshrrev_b32_e32 v1, 22, v1
	s_add_i32 s9, s6, 0xffffff80
	v_lshlrev_b32_e32 v2, 2, v2
	v_add_u32_e32 v1, v3, v1
	s_ashr_i32 s6, s9, 31
	v_lshl_or_b32 v129, s8, 4, v2
	v_ashrrev_i32_e32 v11, 6, v4
	v_and_b32_e32 v1, 0xfffffc00, v1
	s_mul_i32 s6, s0, s6
	s_mul_hi_u32 s7, s0, s9
	v_add_u32_e32 v2, s9, v129
	v_lshlrev_b32_e32 v4, 5, v11
	v_sub_u32_e32 v1, v3, v1
	s_add_i32 s6, s7, s6
	s_mul_i32 s7, s1, s9
	v_ashrrev_i32_e32 v3, 31, v2
	v_and_b32_e32 v12, 32, v4
	s_add_i32 s7, s6, s7
	s_mul_i32 s6, s0, s9
	v_mul_lo_u32 v4, s0, v3
	v_mul_lo_u32 v5, s1, v2
	v_mad_u64_u32 v[2:3], s[8:9], s0, v2, 0
	v_add3_u32 v3, v3, v4, v5
	v_lshl_add_u64 v[4:5], v[2:3], 1, s[4:5]
	v_mov_b32_e32 v2, 0
	v_lshlrev_b32_e32 v6, 4, v44
	v_mov_b32_e32 v7, v2
	v_lshl_add_u64 v[4:5], v[4:5], 0, v[6:7]
	s_mov_b64 s[8:9], 0x1000
	s_lshl_b64 s[6:7], s[6:7], 1
	v_lshl_add_u64 v[6:7], v[4:5], 0, s[8:9]
	s_movk_i32 s8, 0x1000
	s_add_u32 s6, s4, s6
	v_add_co_u32_e32 v4, vcc, s8, v4
	s_addc_u32 s7, s5, s7
	s_nop 0
	v_addc_co_u32_e32 v5, vcc, 0, v5, vcc
	s_lshl_b64 s[8:9], 0x9000, s10
	v_lshl_add_u64 v[8:9], s[0:1], 1, v[6:7]
	s_lshr_b32 s98, s54, 10
	s_lshl_b32 s99, s98, 1
	s_sub_i32 s100, 5, s99
	s_and_b32 s101, s54, 31
	s_lshr_b32 s98, s101, s100
	s_sub_i32 s99, 8, s99
	s_lshl_b32 s98, s98, s99
	s_lshl_b32 s99, -1, s100
	s_andn2_b32 s101, s101, s99
	s_cmp_eq_u32 s101, 0
	s_cselect_b32 s99, 8, 0
	s_lshl_b32 s101, s101, 3
	s_add_i32 s98, s98, s101
	s_add_i32 s98, s98, s99
	s_add_i32 s98, s98, -8
	s_bfe_u32 s101, s54, 0x20008
	s_lshl_b32 s101, s101, 11
	s_add_i32 s98, s98, s101
	s_bfe_u32 s101, s54, 0x30005
	s_lshl_b32 s101, s101, 8
	s_add_i32 s98, s98, s101
	s_mul_i32 s98, s98, 0x9000
	s_lshr_b32 s101, s54, 10
	s_mul_i32 s101, s101, 0x1800
	s_add_i32 s98, s98, s101
	s_add_u32 s98, s36, s98
	s_addc_u32 s99, s37, 0
	v_lshrrev_b32_e32 v240, 4, v129
	v_and_b32_e32 v241, 15, v129
	v_mul_u32_u24_e32 v240, 0x9000, v240
	v_lshl_add_u32 v240, v241, 8, v240
	v_lshl_add_u32 v240, v44, 4, v240
	v_add_u32_e32 v240, 0x12000800, v240
	v_mov_b32_e32 v241, 0
	v_lshl_add_u64 v[4:5], s[98:99], 0, v[240:241]
	global_load_dwordx4 v[22:25], v[4:5], off
	v_lshrrev_b32_e32 v240, 4, v129
	v_and_b32_e32 v241, 15, v129
	v_mul_u32_u24_e32 v240, 0x9000, v240
	v_lshl_add_u32 v240, v241, 8, v240
	v_lshl_add_u32 v240, v44, 4, v240
	v_add_u32_e32 v240, 0x12000900, v240
	v_mov_b32_e32 v241, 0
	v_lshl_add_u64 v[8:9], s[98:99], 0, v[240:241]
	global_load_dwordx4 v[26:29], v[8:9], off
	v_lshl_add_u64 v[4:5], s[8:9], 1, v[6:7]
	v_lshrrev_b32_e32 v240, 4, v129
	v_and_b32_e32 v241, 15, v129
	v_mul_u32_u24_e32 v240, 0x9000, v240
	v_lshl_add_u32 v240, v241, 8, v240
	v_lshl_add_u32 v240, v44, 4, v240
	v_add_u32_e32 v240, 0x12000a00, v240
	v_mov_b32_e32 v241, 0
	v_lshl_add_u64 v[4:5], s[98:99], 0, v[240:241]
	global_load_dwordx4 v[30:33], v[4:5], off
	v_mad_u64_u32 v[4:5], s[8:9], s0, 6, v[6:7]
	v_mov_b32_e32 v6, v5
	v_mad_u64_u32 v[6:7], s[8:9], s1, 6, v[6:7]
	v_mov_b32_e32 v5, v6
	v_lshrrev_b32_e32 v240, 4, v129
	v_and_b32_e32 v241, 15, v129
	v_mul_u32_u24_e32 v240, 0x9000, v240
	v_lshl_add_u32 v240, v241, 8, v240
	v_lshl_add_u32 v240, v44, 4, v240
	v_add_u32_e32 v240, 0x12000b00, v240
	v_mov_b32_e32 v241, 0
	v_lshl_add_u64 v[4:5], s[98:99], 0, v[240:241]
	global_load_dwordx4 v[34:37], v[4:5], off
	v_lshrrev_b32_e32 v3, 4, v1
	v_bitop3_b32 v1, v3, v1, 32 bitop3:0x6c
	v_ashrrev_i32_e32 v3, 31, v1
	v_lshrrev_b32_e32 v3, 26, v3
	v_add_u32_e32 v3, v1, v3
	v_ashrrev_i32_e32 v4, 6, v3
	v_and_b32_e32 v3, 0xc0, v3
	v_sub_u32_e32 v1, v1, v3
	v_ashrrev_i16_sdwa v1, v10, sext(v1) dst_sel:DWORD dst_unused:UNUSED_PAD src0_sel:DWORD src1_sel:BYTE_0
	v_add_u32_sdwa v126, v12, sext(v1) dst_sel:DWORD dst_unused:UNUSED_PAD src0_sel:DWORD src1_sel:WORD_0
	v_lshlrev_b32_e32 v1, 3, v11
	v_and_b32_e32 v1, -16, v1
	v_add_u32_e32 v128, v4, v1
	v_ashrrev_i32_e32 v1, 31, v128
	v_mul_lo_u32 v3, s0, v1
	v_mul_lo_u32 v6, s1, v128
	v_mad_u64_u32 v[4:5], s[8:9], s0, v128, 0
	v_add3_u32 v5, v5, v3, v6
	v_lshl_add_u64 v[4:5], v[4:5], 1, s[6:7]
	v_ashrrev_i32_e32 v127, 31, v126
	v_lshl_add_u64 v[4:5], v[126:127], 1, v[4:5]
	s_mov_b64 s[16:17], 0x800
	s_add_i32 s3, s3, 0
	v_lshl_add_u64 v[6:7], v[4:5], 0, s[16:17]
	s_mov_b32 m0, s3
	v_ashrrev_i32_e32 v121, 31, v124
	v_lshrrev_b32_e32 v240, 4, v128
	v_and_b32_e32 v241, 15, v128
	v_mul_u32_u24_e32 v240, 0x9000, v240
	v_lshl_add_u32 v240, v241, 8, v240
	v_lshl_add_u32 v240, v126, 1, v240
	v_add_u32_e32 v240, 0x800, v240
	v_mov_b32_e32 v241, 0
	v_lshl_add_u64 v[6:7], s[98:99], 0, v[240:241]
	global_load_lds_dwordx4 v[6:7], off
	v_mul_lo_u32 v3, s0, v121
	v_mul_lo_u32 v8, s1, v124
	v_mad_u64_u32 v[6:7], s[8:9], s0, v124, 0
	v_add3_u32 v7, v7, v3, v8
	v_lshl_add_u64 v[6:7], v[6:7], 1, s[6:7]
	v_ashrrev_i32_e32 v123, 31, v122
	v_lshl_add_u64 v[6:7], v[122:123], 1, v[6:7]
	s_add_i32 s6, s3, 0x2000
	v_lshl_add_u64 v[8:9], v[6:7], 0, s[16:17]
	v_writelane_b32 v222, s6, 23
	s_mov_b32 m0, s6
	s_mov_b64 s[60:61], 0x880
	s_add_i32 s6, s3, 0x4000
	v_lshrrev_b32_e32 v240, 4, v124
	v_and_b32_e32 v241, 15, v124
	v_mul_u32_u24_e32 v240, 0x9000, v240
	v_lshl_add_u32 v240, v241, 8, v240
	v_lshl_add_u32 v240, v122, 1, v240
	v_add_u32_e32 v240, 0x800, v240
	v_mov_b32_e32 v241, 0
	v_lshl_add_u64 v[8:9], s[98:99], 0, v[240:241]
	global_load_lds_dwordx4 v[8:9], off
	v_lshl_add_u64 v[4:5], v[4:5], 0, s[60:61]
	v_writelane_b32 v222, s6, 24
	s_mov_b32 m0, s6
	s_add_i32 s6, s3, 0x6000
	v_lshrrev_b32_e32 v240, 4, v128
	v_and_b32_e32 v241, 15, v128
	v_mul_u32_u24_e32 v240, 0x9000, v240
	v_lshl_add_u32 v240, v241, 8, v240
	v_lshl_add_u32 v240, v126, 1, v240
	v_add_u32_e32 v240, 0x880, v240
	v_mov_b32_e32 v241, 0
	v_lshl_add_u64 v[4:5], s[98:99], 0, v[240:241]
	global_load_lds_dwordx4 v[4:5], off
	v_lshl_add_u64 v[4:5], v[6:7], 0, s[60:61]
	s_mov_b32 m0, s6
	v_lshl_add_u32 v3, s11, 7, v125
	v_lshrrev_b32_e32 v240, 4, v124
	v_and_b32_e32 v241, 15, v124
	v_mul_u32_u24_e32 v240, 0x9000, v240
	v_lshl_add_u32 v240, v241, 8, v240
	v_lshl_add_u32 v240, v122, 1, v240
	v_add_u32_e32 v240, 0x880, v240
	v_mov_b32_e32 v241, 0
	v_lshl_add_u64 v[4:5], s[98:99], 0, v[240:241]
	global_load_lds_dwordx4 v[4:5], off
	v_ashrrev_i32_e32 v4, 31, v3
	v_mul_lo_u32 v6, s0, v4
	v_mul_lo_u32 v7, s1, v3
	v_mad_u64_u32 v[4:5], s[0:1], s0, v3, 0
	v_add3_u32 v5, v5, v6, v7
	v_lshl_add_u64 v[4:5], v[4:5], 1, s[4:5]
	v_mov_b32_e32 v119, v2
	v_lshl_add_u64 v[4:5], v[4:5], 0, v[118:119]
	v_readfirstlane_b32 s25, v13
	global_load_dwordx4 v[14:17], v[4:5], off
	global_load_dwordx4 v[10:13], v[4:5], off offset:64
	global_load_dwordx4 v[18:21], v[4:5], off offset:128
	global_load_dwordx4 v[6:9], v[4:5], off offset:192
	s_movk_i32 s0, 0x880
	v_mad_u32_u24 v3, v44, s0, 0
	s_waitcnt vmcnt(0)
	v_and_b32_e32 v4, 0xffff, v22
	v_lshrrev_b32_e32 v22, 16, v22
	s_mov_b32 s24, 0xffff0000
	v_add_u32_e32 v3, v3, v42
	v_and_b32_e32 v5, 0xffff, v30
	v_and_or_b32 v38, v26, s24, v22
	v_lshrrev_b32_e32 v22, 16, v30
	v_lshl_or_b32 v4, v26, 16, v4
	v_add_u32_e32 v119, 0x8000, v3
	v_and_b32_e32 v3, 0xffff, v23
	v_lshl_or_b32 v5, v34, 16, v5
	v_and_or_b32 v39, v34, s24, v22
	ds_write2_b64 v119, v[4:5], v[38:39] offset1:34
	v_lshl_or_b32 v4, v27, 16, v3
	v_and_b32_e32 v3, 0xffff, v31
	v_lshl_or_b32 v5, v35, 16, v3
	v_lshrrev_b32_e32 v3, 16, v23
	v_and_or_b32 v22, v27, s24, v3
	v_lshrrev_b32_e32 v3, 16, v31
	v_and_or_b32 v23, v35, s24, v3
	v_and_b32_e32 v3, 0xffff, v24
	ds_write2_b64 v119, v[4:5], v[22:23] offset0:68 offset1:102
	v_lshl_or_b32 v4, v28, 16, v3
	v_and_b32_e32 v3, 0xffff, v32
	v_lshl_or_b32 v5, v36, 16, v3
	v_lshrrev_b32_e32 v3, 16, v24
	v_and_or_b32 v22, v28, s24, v3
	v_lshrrev_b32_e32 v3, 16, v32
	v_and_or_b32 v23, v36, s24, v3
	v_and_b32_e32 v3, 0xffff, v25
	ds_write2_b64 v119, v[4:5], v[22:23] offset0:136 offset1:170
	v_lshl_or_b32 v4, v29, 16, v3
	v_and_b32_e32 v3, 0xffff, v33
	v_lshl_or_b32 v5, v37, 16, v3
	v_lshrrev_b32_e32 v3, 16, v25
	v_and_or_b32 v22, v29, s24, v3
	v_lshrrev_b32_e32 v3, 16, v33
	v_and_or_b32 v23, v37, s24, v3
	ds_write2_b64 v119, v[4:5], v[22:23] offset0:204 offset1:238
	v_or_b32_e32 v4, 0x60, v40
	v_sub_u32_e32 v136, v4, v120
	v_or_b32_e32 v4, 0x50, v40
	v_sub_u32_e32 v137, v4, v120
	v_or_b32_e32 v4, 64, v40
	v_sub_u32_e32 v138, v4, v120
	v_or_b32_e32 v4, 48, v40
	v_sub_u32_e32 v139, v4, v120
	v_or_b32_e32 v4, 32, v40
	v_sub_u32_e32 v140, v4, v120
	v_or_b32_e32 v4, 16, v40
	v_sub_u32_e32 v141, v4, v120
	v_or_b32_e32 v4, 0xf0, v40
	v_sub_u32_e32 v143, v4, v120
	v_or_b32_e32 v4, 0xe0, v40
	v_sub_u32_e32 v144, v4, v120
	v_or_b32_e32 v4, 0xd0, v40
	v_sub_u32_e32 v145, v4, v120
	v_or_b32_e32 v4, 0xc0, v40
	v_sub_u32_e32 v147, v4, v120
	v_or_b32_e32 v4, 0xb0, v40
	v_writelane_b32 v222, s6, 25
	v_sub_u32_e32 v148, v4, v120
	v_or_b32_e32 v4, 0xa0, v40
	v_cmp_eq_u32_e64 s[4:5], 0, v41
	v_sub_u32_e32 v149, v4, v120
	v_or_b32_e32 v4, 0x90, v40
	v_writelane_b32 v222, s4, 26
	v_sub_u32_e32 v150, v4, v120
	v_or_b32_e32 v4, 0x80, v40
	v_writelane_b32 v222, s5, 27
	s_add_i32 s4, 0, 0x18800
	v_sub_u32_e32 v151, v4, v120
	v_mov_b32_e32 v4, s4
	v_or_b32_e32 v3, 0x70, v40
	v_mad_u32_u24 v4, v44, s0, v4
	s_add_i32 s0, 0, 0x10800
	v_sub_u32_e32 v133, v3, v120
	v_mul_u32_u24_e32 v3, 0x110, v40
	v_add_u32_e32 v152, s0, v43
	s_add_i32 s0, 0, 0x18840
	s_movk_i32 s1, 0x110
	v_add3_u32 v135, 0, v3, v118
	v_add3_u32 v153, s4, v3, v118
	v_mov_b32_e32 v3, s0
	s_add_i32 s0, 0, 0x18880
	v_mad_u32_u24 v154, v40, s1, v3
	v_mov_b32_e32 v3, s0
	s_add_i32 s0, 0, 0x188c0
	v_mad_u32_u24 v155, v40, s1, v3
	v_mov_b32_e32 v3, s0
	v_mad_u32_u24 v156, v40, s1, v3
	s_mov_b32 s1, 0x42800000
	v_writelane_b32 v222, s0, 28
	s_waitcnt vmcnt(0) expcnt(0) lgkmcnt(0)
	s_barrier
	v_writelane_b32 v222, s1, 29
	s_mov_b32 s1, 2.0
	v_writelane_b32 v222, s0, 30
	s_mov_b32 s56, 0x3e0293ee
	v_mbcnt_lo_u32_b32 v3, -1, 0
	v_writelane_b32 v222, s1, 31
	s_mov_b32 s1, 0x40400000
	s_mov_b32 s49, 0
	v_lshlrev_b32_e32 v130, 3, v44
	v_lshlrev_b32_e32 v132, 3, v41
	v_add_u32_e32 v131, 0, v43
	v_sub_u32_e32 v134, v120, v40
	v_sub_u32_e32 v142, v40, v120
	v_mov_b32_e32 v157, 0xf149f2ca
	s_mov_b32 s57, 0x3fb8aa3b
	v_writelane_b32 v222, s0, 32
	s_mov_b32 s63, 0x41800000
	s_mov_b32 s65, 0x41880000
	s_mov_b32 s67, 0x41900000
	s_mov_b32 s69, 0x41980000
	s_mov_b32 s71, 0x42000000
	s_mov_b32 s73, 0x42040000
	s_mov_b32 s75, 0x42080000
	s_mov_b32 s77, 0x420c0000
	s_mov_b32 s79, 0x42400000
	s_mov_b32 s81, 0x42440000
	s_mov_b32 s83, 0x42480000
	s_mov_b32 s85, 0x424c0000
	s_mov_b32 s87, 0x42820000
	s_mov_b32 s89, 0x42840000
	s_mov_b32 s91, 0x42860000
	s_mov_b32 s93, 0x42a00000
	s_mov_b32 s95, 0x42a20000
	s_mov_b32 s97, 0x42a40000
	s_mov_b32 s21, 0x42a60000
	s_mov_b32 s11, 0x42c00000
	s_mov_b32 s43, 0x42c20000
	s_mov_b32 s19, 0x42c40000
	s_mov_b32 s47, 0x42c60000
	s_mov_b32 s45, 0x42e00000
	s_mov_b32 s17, 0x42e20000
	s_mov_b32 s51, 0x42e40000
	s_mov_b32 s53, 0x42e60000
	v_add_u32_e32 v158, v4, v42
	v_mov_b32_e32 v159, 0x42800000
	v_mbcnt_hi_u32_b32 v160, -1, v3
	v_mov_b32_e32 v162, 0xf149f2ca
	v_mov_b32_e32 v164, 0
	v_mov_b32_e32 v58, 0
	v_mov_b32_e32 v59, v2
	v_mov_b32_e32 v60, v2
	v_mov_b32_e32 v61, v2
	v_mov_b32_e32 v54, 0
	v_mov_b32_e32 v55, v2
	v_mov_b32_e32 v56, v2
	v_mov_b32_e32 v57, v2
	v_mov_b32_e32 v62, 0
	v_mov_b32_e32 v63, v2
	v_mov_b32_e32 v64, v2
	v_mov_b32_e32 v65, v2
	v_mov_b32_e32 v66, 0
	v_mov_b32_e32 v67, v2
	v_mov_b32_e32 v68, v2
	v_mov_b32_e32 v69, v2
	v_mov_b32_e32 v70, 0
	v_mov_b32_e32 v71, v2
	v_mov_b32_e32 v72, v2
	v_mov_b32_e32 v73, v2
	v_mov_b32_e32 v74, 0
	v_mov_b32_e32 v75, v2
	v_mov_b32_e32 v76, v2
	v_mov_b32_e32 v77, v2
	v_mov_b32_e32 v78, 0
	v_mov_b32_e32 v79, v2
	v_mov_b32_e32 v80, v2
	v_mov_b32_e32 v81, v2
	v_mov_b32_e32 v82, 0
	v_mov_b32_e32 v83, v2
	v_mov_b32_e32 v84, v2
	v_mov_b32_e32 v85, v2
	v_writelane_b32 v222, s1, 33
	s_branch .LBB0_675

.LBB0_678:
	s_cmpk_lt_i32 s55, 0xc00
	v_mov_b32_e32 v86, 0
	s_cselect_b64 s[4:5], -1, 0
	s_cmpk_gt_i32 s55, 0xbff
	v_mov_b32_e32 v87, 0
	v_mov_b32_e32 v88, 0
	v_mov_b32_e32 v89, 0
	v_mov_b32_e32 v90, 0
	v_mov_b32_e32 v91, 0
	v_mov_b32_e32 v92, 0
	v_mov_b32_e32 v93, 0
	v_mov_b32_e32 v94, 0
	v_mov_b32_e32 v95, 0
	v_mov_b32_e32 v96, 0
	v_mov_b32_e32 v97, 0
	v_mov_b32_e32 v98, 0
	v_mov_b32_e32 v99, 0
	v_mov_b32_e32 v100, 0
	v_mov_b32_e32 v101, 0
	s_cbranch_scc1 .LBB0_680
	s_lshr_b32 s98, s55, 10
	s_lshl_b32 s99, s98, 1
	s_sub_i32 s100, 5, s99
	s_and_b32 s101, s55, 31
	s_lshr_b32 s98, s101, s100
	s_sub_i32 s99, 8, s99
	s_lshl_b32 s98, s98, s99
	s_lshl_b32 s99, -1, s100
	s_andn2_b32 s101, s101, s99
	s_lshl_b32 s99, s40, 3
	s_lshl_b32 s101, s101, 3
	s_add_i32 s98, s98, s101
	s_add_i32 s98, s98, s99
	s_add_i32 s98, s98, -8
	s_bfe_u32 s101, s55, 0x20008
	s_lshl_b32 s101, s101, 11
	s_add_i32 s98, s98, s101
	s_bfe_u32 s101, s55, 0x30005
	s_lshl_b32 s101, s101, 8
	s_add_i32 s98, s98, s101
	s_mul_i32 s98, s98, 0x9000
	s_lshr_b32 s101, s55, 10
	s_mul_i32 s101, s101, 0x1800
	s_add_i32 s98, s98, s101
	s_add_u32 s98, s36, s98
	s_addc_u32 s99, s37, 0
	s_ashr_i32 s6, s55, 10
	s_lshl_b32 s10, s6, 1
	s_sub_i32 s1, 5, s10
	s_and_b32 s0, s55, 31
	s_lshl_b32 s7, -1, s1
	s_lshl_b32 s9, s55, 4
	s_andn2_b32 s8, s0, s7
	s_lshr_b32 s7, s0, s1
	s_and_b32 s9, s9, 0x3000
	s_or_b32 s7, s7, s9
	s_lshl_b64 s[0:1], 0x4800, s10
	s_mul_i32 s7, s7, 0x9000
	s_add_u32 s9, s36, s7
	s_mulk_i32 s6, 0xc00
	s_addc_u32 s16, s37, 0
	s_ashr_i32 s7, s6, 31
	s_lshl_b64 s[6:7], s[6:7], 1
	s_add_u32 s6, s9, s6
	s_addc_u32 s7, s16, s7
	s_lshl_b32 s9, s55, 3
	s_and_b32 s9, s9, 0x700
	s_add_u32 s6, s6, s9
	s_addc_u32 s7, s7, 0
	s_lshl_b32 s9, s40, 7
	s_lshl_b32 s8, s8, 7
	s_xor_b32 s9, s9, 0x80
	s_sub_i32 s16, s8, s9
	s_ashr_i32 s8, s16, 31
	s_mul_i32 s8, s0, s8
	s_mul_hi_u32 s9, s0, s16
	s_add_i32 s8, s9, s8
	s_mul_i32 s9, s1, s16
	s_add_i32 s9, s8, s9
	s_mul_i32 s8, s0, s16
	s_lshl_b64 s[8:9], s[8:9], 1
	s_add_u32 s8, s6, s8
	v_mul_lo_u32 v3, s1, v128
	v_mul_lo_u32 v22, s0, v1
	v_mad_u64_u32 v[4:5], vcc, s0, v128, 0
	s_addc_u32 s9, s7, s9
	v_add3_u32 v5, v5, v22, v3
	v_lshl_add_u64 v[4:5], v[4:5], 1, s[8:9]
	v_lshl_add_u64 v[4:5], v[126:127], 1, v[4:5]
	s_mov_b64 s[58:59], 0x800
	v_lshl_add_u64 v[22:23], v[4:5], 0, s[58:59]
	s_add_i32 m0, s3, 0x10800
	v_mul_lo_u32 v3, s1, v124
	v_lshrrev_b32_e32 v240, 4, v128
	v_and_b32_e32 v241, 15, v128
	v_mul_u32_u24_e32 v240, 0x9000, v240
	v_lshl_add_u32 v240, v241, 8, v240
	v_lshl_add_u32 v240, v126, 1, v240
	v_add_u32_e32 v240, 0x800, v240
	v_mov_b32_e32 v241, 0
	v_lshl_add_u64 v[22:23], s[98:99], 0, v[240:241]
	global_load_lds_dwordx4 v[22:23], off
	v_mul_lo_u32 v24, s0, v121
	v_mad_u64_u32 v[22:23], vcc, s0, v124, 0
	v_add3_u32 v23, v23, v24, v3
	v_lshl_add_u64 v[22:23], v[22:23], 1, s[8:9]
	v_lshl_add_u64 v[22:23], v[122:123], 1, v[22:23]
	v_lshl_add_u64 v[24:25], v[22:23], 0, s[58:59]
	s_add_i32 m0, s3, 0x12800
	v_lshl_add_u64 v[4:5], v[4:5], 0, s[60:61]
	v_lshrrev_b32_e32 v240, 4, v124
	v_and_b32_e32 v241, 15, v124
	v_mul_u32_u24_e32 v240, 0x9000, v240
	v_lshl_add_u32 v240, v241, 8, v240
	v_lshl_add_u32 v240, v122, 1, v240
	v_add_u32_e32 v240, 0x800, v240
	v_mov_b32_e32 v241, 0
	v_lshl_add_u64 v[24:25], s[98:99], 0, v[240:241]
	global_load_lds_dwordx4 v[24:25], off
	s_add_i32 m0, s3, 0x14800
	v_add_u32_e32 v3, s16, v129
	v_lshrrev_b32_e32 v240, 4, v128
	v_and_b32_e32 v241, 15, v128
	v_mul_u32_u24_e32 v240, 0x9000, v240
	v_lshl_add_u32 v240, v241, 8, v240
	v_lshl_add_u32 v240, v126, 1, v240
	v_add_u32_e32 v240, 0x880, v240
	v_mov_b32_e32 v241, 0
	v_lshl_add_u64 v[4:5], s[98:99], 0, v[240:241]
	global_load_lds_dwordx4 v[4:5], off
	v_lshl_add_u64 v[4:5], v[22:23], 0, s[60:61]
	s_add_i32 m0, s3, 0x16800
	v_mul_lo_u32 v23, s1, v3
	v_lshrrev_b32_e32 v240, 4, v124
	v_and_b32_e32 v241, 15, v124
	v_mul_u32_u24_e32 v240, 0x9000, v240
	v_lshl_add_u32 v240, v241, 8, v240
	v_lshl_add_u32 v240, v122, 1, v240
	v_add_u32_e32 v240, 0x880, v240
	v_mov_b32_e32 v241, 0
	v_lshl_add_u64 v[4:5], s[98:99], 0, v[240:241]
	global_load_lds_dwordx4 v[4:5], off
	v_ashrrev_i32_e32 v4, 31, v3
	v_mul_lo_u32 v22, s0, v4
	v_mad_u64_u32 v[4:5], s[8:9], s0, v3, 0
	v_add3_u32 v5, v5, v22, v23
	v_lshl_add_u64 v[4:5], v[4:5], 1, s[6:7]
	v_lshlrev_b32_e32 v22, 1, v130
	v_mov_b32_e32 v23, v2
	v_lshl_add_u64 v[4:5], v[4:5], 0, v[22:23]
	s_mov_b64 s[6:7], 0x1000
	v_lshl_add_u64 v[22:23], v[4:5], 0, s[6:7]
	s_movk_i32 s6, 0x1000
	v_add_co_u32_e32 v4, vcc, s6, v4
	s_lshl_b64 s[6:7], 0x9000, s10
	s_nop 0
	v_addc_co_u32_e32 v5, vcc, 0, v5, vcc
	v_lshl_add_u64 v[24:25], s[0:1], 1, v[22:23]
	v_lshrrev_b32_e32 v240, 4, v129
	v_and_b32_e32 v241, 15, v129
	v_mul_u32_u24_e32 v240, 0x9000, v240
	v_lshl_add_u32 v240, v241, 8, v240
	v_lshl_add_u32 v240, v130, 1, v240
	v_add_u32_e32 v240, 0x12000800, v240
	v_mov_b32_e32 v241, 0
	v_lshl_add_u64 v[4:5], s[98:99], 0, v[240:241]
	global_load_dwordx4 v[86:89], v[4:5], off
	v_lshrrev_b32_e32 v240, 4, v129
	v_and_b32_e32 v241, 15, v129
	v_mul_u32_u24_e32 v240, 0x9000, v240
	v_lshl_add_u32 v240, v241, 8, v240
	v_lshl_add_u32 v240, v130, 1, v240
	v_add_u32_e32 v240, 0x12000900, v240
	v_mov_b32_e32 v241, 0
	v_lshl_add_u64 v[24:25], s[98:99], 0, v[240:241]
	global_load_dwordx4 v[90:93], v[24:25], off
	v_lshl_add_u64 v[4:5], s[6:7], 1, v[22:23]
	v_mad_u64_u32 v[22:23], s[6:7], s0, 6, v[22:23]
	v_mov_b32_e32 v24, v23
	v_mad_u64_u32 v[24:25], s[0:1], s1, 6, v[24:25]
	v_mov_b32_e32 v23, v24
	v_lshrrev_b32_e32 v240, 4, v129
	v_and_b32_e32 v241, 15, v129
	v_mul_u32_u24_e32 v240, 0x9000, v240
	v_lshl_add_u32 v240, v241, 8, v240
	v_lshl_add_u32 v240, v130, 1, v240
	v_add_u32_e32 v240, 0x12000a00, v240
	v_mov_b32_e32 v241, 0
	v_lshl_add_u64 v[4:5], s[98:99], 0, v[240:241]
	global_load_dwordx4 v[94:97], v[4:5], off
	v_lshrrev_b32_e32 v240, 4, v129
	v_and_b32_e32 v241, 15, v129
	v_mul_u32_u24_e32 v240, 0x9000, v240
	v_lshl_add_u32 v240, v241, 8, v240
	v_lshl_add_u32 v240, v130, 1, v240
	v_add_u32_e32 v240, 0x12000b00, v240
	v_mov_b32_e32 v241, 0
	v_lshl_add_u64 v[22:23], s[98:99], 0, v[240:241]
	global_load_dwordx4 v[98:101], v[22:23], off

.LBB0_821:
	s_cmpk_lt_i32 s54, 0xc00
	s_cselect_b64 s[4:5], -1, 0
	s_cmpk_gt_i32 s54, 0xbff
	s_cselect_b64 s[8:9], -1, 0
	v_mov_b32_e32 v86, 0
	s_and_b64 vcc, exec, s[8:9]
	v_mov_b32_e32 v87, 0
	v_mov_b32_e32 v88, 0
	v_mov_b32_e32 v89, 0
	v_mov_b32_e32 v90, 0
	v_mov_b32_e32 v91, 0
	v_mov_b32_e32 v92, 0
	v_mov_b32_e32 v93, 0
	v_mov_b32_e32 v94, 0
	v_mov_b32_e32 v95, 0
	v_mov_b32_e32 v96, 0
	v_mov_b32_e32 v97, 0
	v_mov_b32_e32 v98, 0
	v_mov_b32_e32 v99, 0
	v_mov_b32_e32 v100, 0
	v_mov_b32_e32 v101, 0
	s_cbranch_vccnz .LBB0_823
	s_lshr_b32 s98, s54, 10
	s_lshl_b32 s99, s98, 1
	s_sub_i32 s100, 5, s99
	s_and_b32 s101, s54, 31
	s_lshr_b32 s98, s101, s100
	s_sub_i32 s99, 8, s99
	s_lshl_b32 s98, s98, s99
	s_lshl_b32 s99, -1, s100
	s_andn2_b32 s101, s101, s99
	s_lshl_b32 s99, s25, 3
	s_lshl_b32 s101, s101, 3
	s_add_i32 s98, s98, s101
	s_add_i32 s98, s98, s99
	s_add_i32 s98, s98, -8
	s_bfe_u32 s101, s54, 0x20008
	s_lshl_b32 s101, s101, 11
	s_add_i32 s98, s98, s101
	s_bfe_u32 s101, s54, 0x30005
	s_lshl_b32 s101, s101, 8
	s_add_i32 s98, s98, s101
	s_mul_i32 s98, s98, 0x9000
	s_lshr_b32 s101, s54, 10
	s_mul_i32 s101, s101, 0x1800
	s_add_i32 s98, s98, s101
	s_add_u32 s98, s36, s98
	s_addc_u32 s99, s37, 0
	s_ashr_i32 s6, s54, 10
	s_lshl_b32 s10, s6, 1
	s_sub_i32 s1, 5, s10
	s_and_b32 s0, s54, 31
	s_lshl_b32 s7, -1, s1
	s_lshl_b32 s18, s54, 4
	s_andn2_b32 s16, s0, s7
	s_lshr_b32 s7, s0, s1
	s_and_b32 s18, s18, 0x3000
	s_or_b32 s7, s7, s18
	s_lshl_b64 s[0:1], 0x4800, s10
	s_mul_i32 s7, s7, 0x9000
	s_add_u32 s18, s36, s7
	s_mulk_i32 s6, 0xc00
	s_addc_u32 s20, s37, 0
	s_ashr_i32 s7, s6, 31
	s_lshl_b64 s[6:7], s[6:7], 1
	s_add_u32 s6, s18, s6
	s_addc_u32 s7, s20, s7
	s_lshl_b32 s18, s54, 3
	s_and_b32 s18, s18, 0x700
	s_add_u32 s6, s6, s18
	s_addc_u32 s7, s7, 0
	s_add_i32 s16, s16, s25
	s_lshl_b32 s16, s16, 7
	s_addk_i32 s16, 0xff80
	s_ashr_i32 s18, s16, 31
	s_mul_i32 s18, s0, s18
	s_mul_hi_u32 s20, s0, s16
	s_add_i32 s18, s20, s18
	s_mul_i32 s20, s1, s16
	s_add_i32 vcc_hi, s18, s20
	s_mul_i32 vcc_lo, s0, s16
	s_lshl_b64 vcc, vcc, 1
	s_add_u32 vcc_lo, s6, vcc_lo
	v_mul_lo_u32 v3, s1, v128
	v_mul_lo_u32 v54, s0, v1
	v_mad_u64_u32 v[4:5], s[58:59], s0, v128, 0
	s_addc_u32 vcc_hi, s7, vcc_hi
	v_add3_u32 v5, v5, v54, v3
	v_lshl_add_u64 v[4:5], v[4:5], 1, vcc
	v_lshl_add_u64 v[4:5], v[126:127], 1, v[4:5]
	s_mov_b64 s[60:61], 0x800
	s_mov_b32 m0, s3
	v_lshl_add_u64 v[54:55], v[4:5], 0, s[60:61]
	v_lshrrev_b32_e32 v240, 4, v128
	v_and_b32_e32 v241, 15, v128
	v_mul_u32_u24_e32 v240, 0x9000, v240
	v_lshl_add_u32 v240, v241, 8, v240
	v_lshl_add_u32 v240, v126, 1, v240
	v_add_u32_e32 v240, 0x800, v240
	v_mov_b32_e32 v241, 0
	v_lshl_add_u64 v[54:55], s[98:99], 0, v[240:241]
	global_load_lds_dwordx4 v[54:55], off
	v_mul_lo_u32 v3, s1, v124
	v_mul_lo_u32 v56, s0, v121
	v_mad_u64_u32 v[54:55], s[58:59], s0, v124, 0
	v_add3_u32 v55, v55, v56, v3
	v_lshl_add_u64 v[54:55], v[54:55], 1, vcc
	v_lshl_add_u64 v[54:55], v[122:123], 1, v[54:55]
	v_readlane_b32 s18, v222, 23
	v_lshl_add_u64 v[56:57], v[54:55], 0, s[60:61]
	s_mov_b64 s[60:61], 0x880
	s_mov_b32 m0, s18
	v_readlane_b32 s18, v222, 24
	v_lshrrev_b32_e32 v240, 4, v124
	v_and_b32_e32 v241, 15, v124
	v_mul_u32_u24_e32 v240, 0x9000, v240
	v_lshl_add_u32 v240, v241, 8, v240
	v_lshl_add_u32 v240, v122, 1, v240
	v_add_u32_e32 v240, 0x800, v240
	v_mov_b32_e32 v241, 0
	v_lshl_add_u64 v[56:57], s[98:99], 0, v[240:241]
	global_load_lds_dwordx4 v[56:57], off
	v_lshl_add_u64 v[4:5], v[4:5], 0, s[60:61]
	s_mov_b32 m0, s18
	v_readlane_b32 s18, v222, 25
	v_lshrrev_b32_e32 v240, 4, v128
	v_and_b32_e32 v241, 15, v128
	v_mul_u32_u24_e32 v240, 0x9000, v240
	v_lshl_add_u32 v240, v241, 8, v240
	v_lshl_add_u32 v240, v126, 1, v240
	v_add_u32_e32 v240, 0x880, v240
	v_mov_b32_e32 v241, 0
	v_lshl_add_u64 v[4:5], s[98:99], 0, v[240:241]
	global_load_lds_dwordx4 v[4:5], off
	v_lshl_add_u64 v[4:5], v[54:55], 0, s[60:61]
	s_mov_b32 m0, s18
	v_add_u32_e32 v3, s16, v129
	v_lshrrev_b32_e32 v240, 4, v124
	v_and_b32_e32 v241, 15, v124
	v_mul_u32_u24_e32 v240, 0x9000, v240
	v_lshl_add_u32 v240, v241, 8, v240
	v_lshl_add_u32 v240, v122, 1, v240
	v_add_u32_e32 v240, 0x880, v240
	v_mov_b32_e32 v241, 0
	v_lshl_add_u64 v[4:5], s[98:99], 0, v[240:241]
	global_load_lds_dwordx4 v[4:5], off
	v_ashrrev_i32_e32 v4, 31, v3
	v_mul_lo_u32 v54, s0, v4
	v_mul_lo_u32 v55, s1, v3
	v_mad_u64_u32 v[4:5], s[58:59], s0, v3, 0
	v_add3_u32 v5, v5, v54, v55
	v_lshl_add_u64 v[4:5], v[4:5], 1, s[6:7]
	v_lshlrev_b32_e32 v54, 1, v130
	v_mov_b32_e32 v55, v2
	s_movk_i32 s16, 0x1000
	v_lshl_add_u64 v[4:5], v[4:5], 0, v[54:55]
	s_mov_b64 s[6:7], 0x1000
	v_lshl_add_u64 v[54:55], v[4:5], 0, s[6:7]
	v_add_co_u32_e32 v4, vcc, s16, v4
	s_lshl_b64 s[6:7], 0x9000, s10
	s_nop 0
	v_addc_co_u32_e32 v5, vcc, 0, v5, vcc
	v_lshl_add_u64 v[56:57], s[0:1], 1, v[54:55]
	v_lshrrev_b32_e32 v240, 4, v129
	v_and_b32_e32 v241, 15, v129
	v_mul_u32_u24_e32 v240, 0x9000, v240
	v_lshl_add_u32 v240, v241, 8, v240
	v_lshl_add_u32 v240, v130, 1, v240
	v_add_u32_e32 v240, 0x12000800, v240
	v_mov_b32_e32 v241, 0
	v_lshl_add_u64 v[4:5], s[98:99], 0, v[240:241]
	global_load_dwordx4 v[86:89], v[4:5], off
	v_lshrrev_b32_e32 v240, 4, v129
	v_and_b32_e32 v241, 15, v129
	v_mul_u32_u24_e32 v240, 0x9000, v240
	v_lshl_add_u32 v240, v241, 8, v240
	v_lshl_add_u32 v240, v130, 1, v240
	v_add_u32_e32 v240, 0x12000900, v240
	v_mov_b32_e32 v241, 0
	v_lshl_add_u64 v[56:57], s[98:99], 0, v[240:241]
	global_load_dwordx4 v[90:93], v[56:57], off
	v_lshl_add_u64 v[4:5], s[6:7], 1, v[54:55]
	v_mad_u64_u32 v[54:55], s[6:7], s0, 6, v[54:55]
	v_mov_b32_e32 v56, v55
	v_mad_u64_u32 v[56:57], s[0:1], s1, 6, v[56:57]
	v_mov_b32_e32 v55, v56
	v_lshrrev_b32_e32 v240, 4, v129
	v_and_b32_e32 v241, 15, v129
	v_mul_u32_u24_e32 v240, 0x9000, v240
	v_lshl_add_u32 v240, v241, 8, v240
	v_lshl_add_u32 v240, v130, 1, v240
	v_add_u32_e32 v240, 0x12000a00, v240
	v_mov_b32_e32 v241, 0
	v_lshl_add_u64 v[4:5], s[98:99], 0, v[240:241]
	global_load_dwordx4 v[94:97], v[4:5], off
	v_lshrrev_b32_e32 v240, 4, v129
	v_and_b32_e32 v241, 15, v129
	v_mul_u32_u24_e32 v240, 0x9000, v240
	v_lshl_add_u32 v240, v241, 8, v240
	v_lshl_add_u32 v240, v130, 1, v240
	v_add_u32_e32 v240, 0x12000b00, v240
	v_mov_b32_e32 v241, 0
	v_lshl_add_u64 v[54:55], s[98:99], 0, v[240:241]
	global_load_dwordx4 v[98:101], v[54:55], off

	.amdhsa_kernel _Z6mk_fwd4Args
		.amdhsa_group_segment_fixed_size 0
		.amdhsa_private_segment_fixed_size 0
		.amdhsa_kernarg_size 432
		.amdhsa_user_sgpr_count 2
		.amdhsa_user_sgpr_dispatch_ptr 0
		.amdhsa_user_sgpr_queue_ptr 0
		.amdhsa_user_sgpr_kernarg_segment_ptr 1
		.amdhsa_user_sgpr_dispatch_id 0
		.amdhsa_user_sgpr_kernarg_preload_length 0
		.amdhsa_user_sgpr_kernarg_preload_offset 0
		.amdhsa_user_sgpr_private_segment_size 0
		.amdhsa_uses_dynamic_stack 0
		.amdhsa_enable_private_segment 0
		.amdhsa_system_sgpr_workgroup_id_x 1
		.amdhsa_system_sgpr_workgroup_id_y 0
		.amdhsa_system_sgpr_workgroup_id_z 0
		.amdhsa_system_sgpr_workgroup_info 0
		.amdhsa_system_vgpr_workitem_id 0
		.amdhsa_next_free_vgpr 256
		.amdhsa_next_free_sgpr 102
		.amdhsa_accum_offset 256
		.amdhsa_reserve_vcc 1
		.amdhsa_float_round_mode_32 0
		.amdhsa_float_round_mode_16_64 0
		.amdhsa_float_denorm_mode_32 3
		.amdhsa_float_denorm_mode_16_64 3
		.amdhsa_dx10_clamp 1
		.amdhsa_ieee_mode 1
		.amdhsa_fp16_overflow 0
		.amdhsa_tg_split 0
		.amdhsa_exception_fp_ieee_invalid_op 0
		.amdhsa_exception_fp_denorm_src 0
		.amdhsa_exception_fp_ieee_div_zero 0
		.amdhsa_exception_fp_ieee_overflow 0
		.amdhsa_exception_fp_ieee_underflow 0
		.amdhsa_exception_fp_ieee_inexact 0
		.amdhsa_exception_int_div_zero 0
	.end_amdhsa_kernel

amdhsa.kernels:
  - .agpr_count:     0
    .args:
      - .offset:         0
        .size:           176
        .value_kind:     by_value
      - .offset:         176
        .size:           4
        .value_kind:     hidden_block_count_x
      - .offset:         180
        .size:           4
        .value_kind:     hidden_block_count_y
      - .offset:         184
        .size:           4
        .value_kind:     hidden_block_count_z
      - .offset:         188
        .size:           2
        .value_kind:     hidden_group_size_x
      - .offset:         190
        .size:           2
        .value_kind:     hidden_group_size_y
      - .offset:         192
        .size:           2
        .value_kind:     hidden_group_size_z
      - .offset:         194
        .size:           2
        .value_kind:     hidden_remainder_x
      - .offset:         196
        .size:           2
        .value_kind:     hidden_remainder_y
      - .offset:         198
        .size:           2
        .value_kind:     hidden_remainder_z
      - .offset:         216
        .size:           8
        .value_kind:     hidden_global_offset_x
      - .offset:         224
        .size:           8
        .value_kind:     hidden_global_offset_y
      - .offset:         232
        .size:           8
        .value_kind:     hidden_global_offset_z
      - .offset:         240
        .size:           2
        .value_kind:     hidden_grid_dims
      - .offset:         296
        .size:           4
        .value_kind:     hidden_dynamic_lds_size
    .group_segment_fixed_size: 0
    .kernarg_segment_align: 8
    .kernarg_segment_size: 432
    .language:       OpenCL C
    .language_version:
      - 2
      - 0
    .max_flat_workgroup_size: 512
    .name:           _Z6mk_fwd4Args
    .private_segment_fixed_size: 0
    .sgpr_count:     108
    .sgpr_spill_count: 145
    .symbol:         _Z6mk_fwd4Args.kd
    .uniform_work_group_size: 1
    .uses_dynamic_stack: false
    .vgpr_count:     256
    .vgpr_spill_count: 0
    .wavefront_size: 64
